# grid barrier: local arrivers 8, 16 and 24 each start an un-waited L2 write-back
# baseline (speedup 1.0000x reference)
.Lxb0_194:
	s_or_b64 exec, exec, s[12:13]
	v_cvt_f32_u32_e32 v4, v2
	s_waitcnt vmcnt(0)
	v_readfirstlane_b32 s0, v3
	v_sub_u32_e32 v3, 0, v2
	v_rcp_iflag_f32_e32 v4, v4
	v_add_u32_e32 v5, s0, v1
	v_mul_f32_e32 v4, 0x4f7ffffe, v4
	v_cvt_u32_f32_e32 v4, v4
	v_mul_lo_u32 v1, v3, v4
	v_mul_hi_u32 v1, v4, v1
	v_add_u32_e32 v1, v4, v1
	v_mul_hi_u32 v1, v5, v1
	v_mul_lo_u32 v3, v1, v2
	v_sub_u32_e32 v3, v5, v3
	v_add_u32_e32 v4, 1, v1
	v_cmp_ge_u32_e32 vcc, v3, v2
	s_nop 1
	v_cndmask_b32_e32 v1, v1, v4, vcc
	v_sub_u32_e32 v4, v3, v2
	v_cndmask_b32_e32 v3, v3, v4, vcc
	v_add_u32_e32 v4, 1, v1
	v_cmp_ge_u32_e32 vcc, v3, v2
	v_add_u32_e32 v3, 1, v5
	s_nop 0
	v_cndmask_b32_e32 v1, v1, v4, vcc
	v_mul_lo_u32 v4, v2, v1
	v_add_u32_e32 v2, v4, v2
	v_sub_u32_e32 v4, v5, v4
	v_add_u32_e32 v4, -8, v4
	v_and_b32_e32 v4, 0xffffffe7, v4
	v_cmp_eq_u32_e32 vcc, 0, v4
	s_cbranch_vccz .Lefl_0
	buffer_wbl2 sc1

.LBB0_735:
	s_or_b64 exec, exec, s[14:15]
	v_cvt_f32_u32_e32 v4, v2
	s_waitcnt vmcnt(0)
	v_readfirstlane_b32 s0, v3
	v_sub_u32_e32 v3, 0, v2
	v_rcp_iflag_f32_e32 v4, v4
	v_add_u32_e32 v5, s0, v1
	v_mul_f32_e32 v4, 0x4f7ffffe, v4
	v_cvt_u32_f32_e32 v4, v4
	v_mul_lo_u32 v1, v3, v4
	v_mul_hi_u32 v1, v4, v1
	v_add_u32_e32 v1, v4, v1
	v_mul_hi_u32 v1, v5, v1
	v_mul_lo_u32 v3, v1, v2
	v_sub_u32_e32 v3, v5, v3
	v_add_u32_e32 v4, 1, v1
	v_cmp_ge_u32_e32 vcc, v3, v2
	s_nop 1
	v_cndmask_b32_e32 v1, v1, v4, vcc
	v_sub_u32_e32 v4, v3, v2
	v_cndmask_b32_e32 v3, v3, v4, vcc
	v_add_u32_e32 v4, 1, v1
	v_cmp_ge_u32_e32 vcc, v3, v2
	v_add_u32_e32 v3, 1, v5
	s_nop 0
	v_cndmask_b32_e32 v1, v1, v4, vcc
	v_mul_lo_u32 v4, v2, v1
	v_add_u32_e32 v2, v4, v2
	v_sub_u32_e32 v4, v5, v4
	v_add_u32_e32 v4, -8, v4
	v_and_b32_e32 v4, 0xffffffe7, v4
	v_cmp_eq_u32_e32 vcc, 0, v4
	s_cbranch_vccz .Lefl_7
	buffer_wbl2 sc1

.LBB0_1040:
	s_or_b64 exec, exec, s[10:11]
	v_cvt_f32_u32_e32 v4, v2
	s_waitcnt vmcnt(0)
	v_readfirstlane_b32 s3, v3
	v_sub_u32_e32 v3, 0, v2
	v_rcp_iflag_f32_e32 v4, v4
	v_add_u32_e32 v5, s3, v1
	v_mul_f32_e32 v4, 0x4f7ffffe, v4
	v_cvt_u32_f32_e32 v4, v4
	v_mul_lo_u32 v1, v3, v4
	v_mul_hi_u32 v1, v4, v1
	v_add_u32_e32 v1, v4, v1
	v_mul_hi_u32 v1, v5, v1
	v_mul_lo_u32 v3, v1, v2
	v_sub_u32_e32 v3, v5, v3
	v_add_u32_e32 v4, 1, v1
	v_cmp_ge_u32_e32 vcc, v3, v2
	s_nop 1
	v_cndmask_b32_e32 v1, v1, v4, vcc
	v_sub_u32_e32 v4, v3, v2
	v_cndmask_b32_e32 v3, v3, v4, vcc
	v_add_u32_e32 v4, 1, v1
	v_cmp_ge_u32_e32 vcc, v3, v2
	v_add_u32_e32 v3, 1, v5
	s_nop 0
	v_cndmask_b32_e32 v1, v1, v4, vcc
	v_mul_lo_u32 v4, v2, v1
	v_add_u32_e32 v2, v4, v2
	v_sub_u32_e32 v4, v5, v4
	v_add_u32_e32 v4, -8, v4
	v_and_b32_e32 v4, 0xffffffe7, v4
	v_cmp_eq_u32_e32 vcc, 0, v4
	s_cbranch_vccz .Lefl_10
	buffer_wbl2 sc1
